# G1 tile grouping WGM 2->4 (4 rows x 8 cols per XCD round, fewer L2 misses)
# baseline (speedup 1.0000x reference)
;     __device__ __forceinline__ bool next(int i, Unit& u) const {
;     ...
;         int wgid = (int)L; { const int q = nwg / NXCD, r = nwg % NXCD, xcd = wgid % NXCD, off = wgid / NXCD; wgid = (xcd < r ? xcd * (q + 1) : r * (q + 1) + (xcd - r) * q) + off; }
;         const int nig = WGM * nN, gid = wgid / nig, fm = gid * WGM, gsz = (nMe - fm) < WGM ? (nMe - fm) : WGM;
;         u.pm = fm + ((wgid % nig) % gsz); u.pn = (wgid % nig) / gsz; u.kt0 = 0; u.nkt = ktall; return true;
.LBB0_57:
	s_ashr_i32 s0, s2, 3
	s_add_i32 s0, s8, s0
	s_mul_hi_i32 s1, s0, 0x78787879
	s_lshr_b32 s2, s1, 31
	s_ashr_i32 s1, s1, 7
	s_add_i32 s1, s1, s2
	s_lshl_b32 s2, s1, 2
	s_sub_i32 s3, 33, s2
	s_min_u32 s3, s3, 4
	s_mulk_i32 s1, 0x110
	s_sub_i32 s8, s0, s1
	v_cvt_f32_ubyte0_e32 v1, s3
	v_cvt_f32_i32_e32 v0, s8
	v_rcp_iflag_f32_e32 v2, v1
	s_ashr_i32 s0, s8, 30
	s_or_b32 s9, s0, 1
	v_mul_f32_e32 v2, v0, v2
	v_trunc_f32_e32 v2, v2
	v_fma_f32 v0, -v2, v1, v0
	v_cvt_i32_f32_e32 v2, v2
	v_cmp_ge_f32_e64 s[0:1], |v0|, v1
	s_and_b64 s[0:1], s[0:1], exec
	s_cselect_b32 s0, s9, 0
	v_readfirstlane_b32 s1, v2
	s_add_i32 s1, s1, s0
	s_sext_i32_i16 s0, s1
	s_mul_i32 s1, s1, s3
	s_sub_i32 s1, s8, s1
	s_sext_i32_i16 s1, s1
	s_add_i32 s2, s2, s1

;     __device__ __forceinline__ bool next(int i, Unit& u) const {
;     ...
;         int wgid = (int)L; { const int q = nwg / NXCD, r = nwg % NXCD, xcd = wgid % NXCD, off = wgid / NXCD; wgid = (xcd < r ? xcd * (q + 1) : r * (q + 1) + (xcd - r) * q) + off; }
;         const int nig = WGM * nN, gid = wgid / nig, fm = gid * WGM, gsz = (nMe - fm) < WGM ? (nMe - fm) : WGM;
;         u.pm = fm + ((wgid % nig) % gsz); u.pn = (wgid % nig) / gsz; u.kt0 = 0; u.nkt = ktall; return true;
.LBB0_69:
	s_ashr_i32 s1, s1, 3
	s_add_i32 s1, s38, s1
	s_mul_hi_i32 s3, s1, 0x78787879
	s_lshr_b32 s14, s3, 31
	s_ashr_i32 s3, s3, 7
	s_add_i32 s3, s3, s14
	s_lshl_b32 s14, s3, 2
	s_sub_i32 s15, 33, s14
	s_min_i32 s15, s15, 4
	s_abs_i32 s38, s15
	v_cvt_f32_u32_e32 v0, s38
	s_sub_i32 s40, 0, s38
	s_mulk_i32 s3, 0x110
	s_sub_i32 s1, s1, s3
	v_rcp_iflag_f32_e32 v0, v0
	s_abs_i32 s3, s1
	s_xor_b32 s39, s1, s15
	s_ashr_i32 s39, s39, 31
	v_mul_f32_e32 v0, 0x4f7ffffe, v0
	v_cvt_u32_f32_e32 v0, v0
	s_nop 0
	v_readfirstlane_b32 s41, v0
	s_mul_i32 s40, s40, s41
	s_mul_hi_u32 s40, s41, s40
	s_add_i32 s41, s41, s40
	s_mul_hi_u32 s40, s3, s41
	s_mul_i32 s41, s40, s38
	s_sub_i32 s3, s3, s41
	s_add_i32 s46, s40, 1
	s_sub_i32 s41, s3, s38
	s_cmp_ge_u32 s3, s38
	s_cselect_b32 s40, s46, s40
	s_cselect_b32 s3, s41, s3
	s_add_i32 s41, s40, 1
	s_cmp_ge_u32 s3, s38
	s_cselect_b32 s3, s41, s40
	s_xor_b32 s3, s3, s39
	s_sub_i32 s46, s3, s39
	s_mul_i32 s3, s46, s15
	s_sub_i32 s1, s1, s3
	s_add_i32 s48, s14, s1
